# last out-proj sample-row tail tiles folded into the final-norm phase (32 workgroups run them while 224 normalise prompt rows; one poller wave per workgroup)
# speedup vs baseline: 1.0345x; 1.0015x over previous
;     __device__ __forceinline__ bool next(int i, Unit& u) const {
;         const long Lx = (long)i * G + c; if (Lx >= nrun) return false;
;         map((int)Lx, u); return true;
;     }
; __global__ void __launch_bounds__(NTHR) mega(Params p) {
;     ...
;     if (IN(7)) {
;         const bool split = (gridDim.x == 256);
;         pg8::Gemm g{(const bf16_t*)(ws + WS_Y2), (const bf16_t*)(ws + WS_WOUTO), T, 1024, 1536, 1536};
;         pg8::StaticOrder S; S.init(T, 1024, gridDim.x, blockIdx.x, split ? 512 : -1);
;         EpiOutResB E{(bf16_t*)(ws + WS_XB), (float*)(ws + WS_RSQ2)};
;         pg8::gemm_phase<EpiOutResB, pg8::StaticOrder>(L, g, S, E);
.Lp7_reenter:
	s_movk_i32 s100, 0x44
	s_cmpk_eq_i32 s94, 0x100
	s_cselect_b32 s100, 0x40, s100
	s_cmpk_eq_i32 s94, 0x100
	s_cselect_b64 s[14:15], -1, 0
	s_movk_i32 s3, 0x200
	s_and_b64 s[0:1], s[14:15], exec
	s_cselect_b32 s16, s3, 0x220
	s_cmp_eq_u32 s101, 3
	s_cbranch_scc0 .Lp7_nrun_ok
	s_add_i32 s16, s2, 1
.Lp7_nrun_ok:
	s_cmp_lt_i32 s2, s16
	s_cselect_b64 s[0:1], -1, 0
	s_cmp_ge_i32 s2, s16
	v_readfirstlane_b32 s4, v136
	s_cbranch_scc1 .LBB0_1404
	s_ashr_i32 s3, s2, 31
	s_lshr_b32 s3, s3, 29
	s_add_i32 s3, s2, s3
	s_ashr_i32 s5, s3, 3
	s_and_b32 s3, s3, -8
	s_sub_i32 s3, s2, s3
	s_cmp_lt_i32 s3, 0
	s_movk_i32 s6, 0x45
	s_cselect_b32 s6, s6, s100
	s_mul_i32 s3, s3, s6
	s_add_i32 s3, s3, s5
	s_ashr_i32 s5, s3, 31
	s_lshr_b32 s5, s5, 27
	s_add_i32 s5, s3, s5
	s_ashr_i32 s6, s5, 5
	s_and_b32 s5, s5, 0xffe0
	s_sub_i32 s3, s3, s5
	s_bfe_i32 s5, s3, 0x80000
	s_bfe_u32 s5, s5, 0x3000c
	s_add_i32 s5, s3, s5
	s_bfe_i32 s7, s5, 0x80000
	s_and_b32 s5, s5, 0xf8
	s_sub_i32 s3, s3, s5
	s_lshl_b32 s6, s6, 3
	s_sext_i32_i16 s7, s7
	s_sext_i32_i8 s3, s3
	s_add_i32 s61, s6, s3
	s_ashr_i32 s60, s7, 3

;     __device__ __forceinline__ bool next(int i, Unit& u) const {
;         const long Lx = (long)i * G + c; if (Lx >= nrun) return false;
;         map((int)Lx, u); return true;
; template <class Epi, class Sched>
; __device__ __forceinline__ void gemm_phase(LAS unsigned char* lds, const Gemm g, const Sched& S, const Epi& E) {
;     ...
;         const bool has_next = S.next(ui + 1, nxt);
;         const char* nA = has_next ? (const char*)g.A + (size_t)nxt.pm * tstep + nxt.koff : cA; const char* nB = has_next ? (const char*)g.Bt + (size_t)nxt.pn * tstep + nxt.koff : cB;
.LBB0_1410:
	s_add_i32 s17, s17, 1
	s_mul_i32 s0, s17, s53
	s_mul_hi_u32 s1, s17, s54
	s_add_i32 s1, s1, s0
	s_mul_i32 s0, s17, s54
	s_add_u32 s6, s0, s2
	s_addc_u32 s7, s1, s55
	v_cmp_ge_i64_e32 vcc, s[6:7], v[140:141]
	v_cmp_lt_i64_e64 s[0:1], s[6:7], v[140:141]
	s_cbranch_vccnz .LBB0_1412
	s_ashr_i32 s7, s6, 31
	s_lshr_b32 s7, s7, 29
	s_add_i32 s7, s6, s7
	s_ashr_i32 s26, s7, 3
	s_and_b32 s7, s7, -8
	s_sub_i32 s6, s6, s7
	s_cmp_lt_i32 s6, 0
	s_cselect_b32 s7, s16, s100
	s_mul_i32 s6, s6, s7
	s_add_i32 s6, s6, s26
	s_ashr_i32 s7, s6, 31
	s_lshr_b32 s7, s7, 27
	s_add_i32 s7, s6, s7
	s_ashr_i32 s26, s7, 5
	s_lshl_b32 s26, s26, 3
	s_sub_i32 s27, 0x88, s26
	s_min_i32 s27, s27, 8
	s_abs_i32 s34, s27
	v_cvt_f32_u32_e32 v0, s34
	s_sub_i32 s58, 0, s34
	s_andn2_b32 s7, s7, 31
	s_sub_i32 s6, s6, s7
	v_rcp_iflag_f32_e32 v0, v0
	s_abs_i32 s7, s6
	s_xor_b32 s35, s6, s27
	s_ashr_i32 s35, s35, 31
	v_mul_f32_e32 v0, 0x4f7ffffe, v0
	v_cvt_u32_f32_e32 v0, v0
	s_nop 0
	v_readfirstlane_b32 s59, v0
	s_mul_i32 s58, s58, s59
	s_mul_hi_u32 s58, s59, s58
	s_add_i32 s59, s59, s58
	s_mul_hi_u32 s58, s7, s59
	s_mul_i32 s59, s58, s34
	s_sub_i32 s7, s7, s59
	s_add_i32 s62, s58, 1
	s_sub_i32 s59, s7, s34
	s_cmp_ge_u32 s7, s34
	s_cselect_b32 s58, s62, s58
	s_cselect_b32 s7, s59, s7
	s_add_i32 s59, s58, 1
	s_cmp_ge_u32 s7, s34
	s_cselect_b32 s7, s59, s58
	s_xor_b32 s7, s7, s35
	s_sub_i32 s58, s7, s35
	s_mul_i32 s7, s58, s27
	s_sub_i32 s6, s6, s7
	s_add_i32 s59, s26, s6

; __global__ void __launch_bounds__(NTHR) mega(Params p) {
;     ...
;         if (split) {
;             pg8::Gemm gs{(const bf16_t*)(ws + WS_Y2), (const bf16_t*)(ws + WS_WOUTO), T, 1024, 256, 1536};
;             pg8::SliceOrder SS{S, 512, 6, 512u};
;             EpiPartial EP{(float*)(ws + WS_Q)};
;             pg8::gemm_phase<EpiPartial, pg8::SliceOrder>(L, gs, SS, EP);
;             xcd_barrier(xb);
;             splitk_reduce(S, 512, 6, (const float*)(ws + WS_Q), (bf16_t*)(ws + WS_XB), (float*)(ws + WS_RSQ2));
;         }
;     }
.LBB0_1440:
	s_cmp_eq_u32 s101, 3
	s_cbranch_scc1 .Lp7_tail_done

; __device__ __forceinline__ float bflo(unsigned w) { return __uint_as_float(w << 16); }
; __device__ __forceinline__ float bfhi(unsigned w) { return __uint_as_float(w & 0xffff0000u); }
; #define SEAM(k) do { if (IN(k) && IN((k) + 1)) xcd_barrier(xb); } while (0)
; __device__ __forceinline__ void phase8(const Params& p) {
;     const float* rsq = (const float*)(p.ws + WS_RSQ2); const float* g = p.in[24]; float* y = p.out; const bf16_t* xb = (const bf16_t*)(p.ws + WS_XB);
;     const long gtid = (long)blockIdx.x * NTHR + threadIdx.x, gsz = (long)gridDim.x * NTHR;
;     const long total = (long)T * 128;
;     for (long it = gtid; it < total; it += gsz) {
;         const long row = it >> 7; const int c8 = (int)(it & 127) * 8;
;         const float rs = rsqrtf(rsq[row] * (1.f / 1024.f) + EPS);
;         const u32x4 xw = *(const u32x4*)(xb + row * 1024 + c8);
;         const f32x4 g0 = *(const f32x4*)(g + c8), g1 = *(const f32x4*)(g + c8 + 4);
;         f32x4 o0, o1;
;         o0[0] = bflo(xw.x) * rs * g0[0]; o0[1] = bfhi(xw.x) * rs * g0[1]; o0[2] = bflo(xw.y) * rs * g0[2]; o0[3] = bfhi(xw.y) * rs * g0[3];
;         o1[0] = bflo(xw.z) * rs * g1[0]; o1[1] = bfhi(xw.z) * rs * g1[1]; o1[2] = bflo(xw.w) * rs * g1[2]; o1[3] = bfhi(xw.w) * rs * g1[3];
;         *(f32x4*)(y + row * 1024 + c8) = o0; *(f32x4*)(y + row * 1024 + c8 + 4) = o1;
;     }
; __global__ void __launch_bounds__(NTHR) mega(Params p) {
;     ...
;     SEAM(7);
;     if (IN(8)) phase8(p);
.LBB0_1559:
	s_cmp_lt_i32 s46, 9
	s_cselect_b64 s[4:5], -1, 0
	s_and_b64 s[0:1], s[4:5], s[0:1]
	s_andn2_b64 vcc, exec, s[0:1]
	s_cbranch_vccnz .LBB0_1563
	s_cmpk_eq_i32 s94, 0x100
	s_cbranch_scc0 .Lp8_generic
	s_cmp_lt_u32 s2, 32
	s_cbranch_scc0 .Lp8_prompt
	s_mov_b32 s99, s2
	s_lshl_b32 s2, s2, 3
	s_add_i32 s2, s2, 0x1000
	s_mov_b32 s101, 3
	s_branch .Lp7_reenter
.Lp7_tail_done:
	s_mov_b32 s2, s99
	s_mov_b32 s101, 4
	v_cmp_eq_u32_e32 vcc, 0, v136
	s_and_saveexec_b64 s[4:5], vcc
	s_cbranch_execz .Lp7_sig_skip
	buffer_wbl2 sc1
	s_waitcnt vmcnt(0)
	s_add_u32 s6, s44, 0x1f711900
	s_addc_u32 s7, s45, 0
	v_mov_b32_e32 v0, 0
	v_mov_b32_e32 v1, 1
	global_atomic_add v0, v1, s[6:7]
	s_waitcnt vmcnt(0)
.Lp7_sig_skip:
	s_or_b64 exec, exec, s[4:5]
	s_mov_b64 s[14:15], 0
	s_branch .Lp8_common
.Lp8_prompt:
	s_mov_b64 s[14:15], -1
.Lp8_common:
	s_add_u32 s0, s44, 0x5e64000
	s_addc_u32 s1, s45, 0
	s_add_u32 s4, s44, 0x1a20000
	s_addc_u32 s5, s45, 0
	v_mov_b32_e32 v28, v136
	v_mov_b32_e32 v137, 0
	v_mov_b32_e32 v4, 0x358637bd
	s_mov_b32 s12, 0x800000
	s_waitcnt lgkmcnt(0)
	s_andn2_b64 vcc, exec, s[14:15]
	s_cbranch_vccnz .Lp8_sample
	s_sub_i32 s3, s2, 32
	s_lshl_b32 s3, s3, 9
	v_add_u32_e32 v0, s3, v28
	v_mov_b32_e32 v1, 0
	s_mov_b32 s6, 0x1c000
	s_mov_b32 s7, 0
	s_mov_b32 s10, 0x3fffff
	s_mov_b32 s11, 0
	s_mov_b64 s[8:9], 0
.Lp8_loop_prompt:
	v_lshrrev_b64 v[18:19], 7, v[0:1]
	v_lshl_add_u64 v[6:7], v[18:19], 2, s[0:1]
	global_load_dword v22, v[6:7], off
	v_and_b32_e32 v5, 0x7f, v0
	v_lshlrev_b32_e32 v5, 3, v5
	v_lshlrev_b64 v[8:9], 11, v[18:19]
	v_lshlrev_b32_e32 v136, 1, v5
	v_lshl_add_u64 v[6:7], s[4:5], 0, v[8:9]
	v_lshl_add_u64 v[20:21], v[6:7], 0, v[136:137]
	v_lshlrev_b32_e32 v136, 2, v5
	global_load_dwordx4 v[6:9], v[20:21], off
	global_load_dwordx4 v[10:13], v136, s[40:41]
	global_load_dwordx4 v[14:17], v136, s[40:41] offset:16
	v_lshl_add_u64 v[0:1], v[0:1], 0, s[6:7]
	v_cmp_lt_u64_e32 vcc, s[10:11], v[0:1]
	s_or_b64 s[8:9], vcc, s[8:9]
	v_lshlrev_b64 v[18:19], 12, v[18:19]
	v_lshl_add_u64 v[18:19], s[42:43], 0, v[18:19]
	v_lshl_add_u64 v[18:19], v[18:19], 0, v[136:137]
	s_waitcnt vmcnt(0)
	v_fmamk_f32 v5, v22, 0x3a800000, v4
	v_mul_f32_e32 v20, 0x4b800000, v5
	v_cmp_gt_f32_e32 vcc, s12, v5
	v_and_b32_e32 v21, 0xffff0000, v6
	s_nop 0
	v_cndmask_b32_e32 v5, v5, v20, vcc
	v_rsq_f32_e32 v5, v5
	v_lshlrev_b32_e32 v20, 16, v6
	v_lshlrev_b32_e32 v6, 16, v7
	v_and_b32_e32 v7, 0xffff0000, v7
	v_mul_f32_e32 v24, 0x45800000, v5
	v_cndmask_b32_e32 v24, v5, v24, vcc
	v_lshlrev_b32_e32 v22, 16, v8
	v_and_b32_e32 v23, 0xffff0000, v8
	v_lshlrev_b32_e32 v8, 16, v9
	v_and_b32_e32 v9, 0xffff0000, v9
	v_pk_mul_f32 v[20:21], v[24:25], v[20:21] op_sel_hi:[0,1]
	v_pk_mul_f32 v[26:27], v[24:25], v[6:7] op_sel_hi:[0,1]
	v_pk_mul_f32 v[22:23], v[24:25], v[22:23] op_sel_hi:[0,1]
	v_pk_mul_f32 v[24:25], v[24:25], v[8:9] op_sel_hi:[0,1]
	v_pk_mul_f32 v[6:7], v[10:11], v[20:21]
	v_pk_mul_f32 v[8:9], v[12:13], v[26:27]
	v_pk_mul_f32 v[10:11], v[14:15], v[22:23]
	v_pk_mul_f32 v[12:13], v[16:17], v[24:25]
	global_store_dwordx4 v[18:19], v[6:9], off
	global_store_dwordx4 v[18:19], v[10:13], off offset:16
	s_andn2_b64 exec, exec, s[8:9]
	s_cbranch_execnz .Lp8_loop_prompt
	s_mov_b64 exec, -1
.Lp8_sample:
	v_readfirstlane_b32 s3, v28
	s_waitcnt vmcnt(0)
	s_cmp_lt_u32 s3, 64
	s_cbranch_scc0 .Lp8_polled
	s_add_u32 s6, s44, 0x1f711900
	s_addc_u32 s7, s45, 0
	v_mov_b32_e32 v0, 0
.Lp8_poll:
	global_load_dword v1, v0, s[6:7] sc1
	s_waitcnt vmcnt(0)
	v_readfirstlane_b32 s3, v1
	s_cmp_ge_u32 s3, 32
	s_cbranch_scc1 .Lp8_poll_ok
	s_sleep 32
	s_branch .Lp8_poll

; __device__ __forceinline__ float bflo(unsigned w) { return __uint_as_float(w << 16); }
; __device__ __forceinline__ float bfhi(unsigned w) { return __uint_as_float(w & 0xffff0000u); }
; __device__ __forceinline__ void phase8(const Params& p) {
;     const float* rsq = (const float*)(p.ws + WS_RSQ2); const float* g = p.in[24]; float* y = p.out; const bf16_t* xb = (const bf16_t*)(p.ws + WS_XB);
;     const long gtid = (long)blockIdx.x * NTHR + threadIdx.x, gsz = (long)gridDim.x * NTHR;
;     const long total = (long)T * 128;
;     for (long it = gtid; it < total; it += gsz) {
;         const long row = it >> 7; const int c8 = (int)(it & 127) * 8;
;         const float rs = rsqrtf(rsq[row] * (1.f / 1024.f) + EPS);
;         const u32x4 xw = *(const u32x4*)(xb + row * 1024 + c8);
;         const f32x4 g0 = *(const f32x4*)(g + c8), g1 = *(const f32x4*)(g + c8 + 4);
;         f32x4 o0, o1;
;         o0[0] = bflo(xw.x) * rs * g0[0]; o0[1] = bfhi(xw.x) * rs * g0[1]; o0[2] = bflo(xw.y) * rs * g0[2]; o0[3] = bfhi(xw.y) * rs * g0[3];
;         o1[0] = bflo(xw.z) * rs * g1[0]; o1[1] = bfhi(xw.z) * rs * g1[1]; o1[2] = bflo(xw.w) * rs * g1[2]; o1[3] = bfhi(xw.w) * rs * g1[3];
;         *(f32x4*)(y + row * 1024 + c8) = o0; *(f32x4*)(y + row * 1024 + c8 + 4) = o1;
;     }
.Lp8_polled:
	s_barrier
	s_lshl_b32 s3, s2, 9
	s_add_i32 s3, s3, 0x400000
	v_add_u32_e32 v0, s3, v28
	v_mov_b32_e32 v1, 0
	s_mov_b32 s6, 0x20000
	s_mov_b32 s7, 0
	s_mov_b32 s10, 0x43ffff
	s_mov_b32 s11, 0
	s_mov_b64 s[8:9], 0
.Lp8_loop_sample:
	v_lshrrev_b64 v[18:19], 7, v[0:1]
	v_lshl_add_u64 v[6:7], v[18:19], 2, s[0:1]
	global_load_dword v22, v[6:7], off
	v_and_b32_e32 v5, 0x7f, v0
	v_lshlrev_b32_e32 v5, 3, v5
	v_lshlrev_b64 v[8:9], 11, v[18:19]
	v_lshlrev_b32_e32 v136, 1, v5
	v_lshl_add_u64 v[6:7], s[4:5], 0, v[8:9]
	v_lshl_add_u64 v[20:21], v[6:7], 0, v[136:137]
	v_lshlrev_b32_e32 v136, 2, v5
	global_load_dwordx4 v[6:9], v[20:21], off
	global_load_dwordx4 v[10:13], v136, s[40:41]
	global_load_dwordx4 v[14:17], v136, s[40:41] offset:16
	v_lshl_add_u64 v[0:1], v[0:1], 0, s[6:7]
	v_cmp_lt_u64_e32 vcc, s[10:11], v[0:1]
	s_or_b64 s[8:9], vcc, s[8:9]
	v_lshlrev_b64 v[18:19], 12, v[18:19]
	v_lshl_add_u64 v[18:19], s[42:43], 0, v[18:19]
	v_lshl_add_u64 v[18:19], v[18:19], 0, v[136:137]
	s_waitcnt vmcnt(0)
	v_fmamk_f32 v5, v22, 0x3a800000, v4
	v_mul_f32_e32 v20, 0x4b800000, v5
	v_cmp_gt_f32_e32 vcc, s12, v5
	v_and_b32_e32 v21, 0xffff0000, v6
	s_nop 0
	v_cndmask_b32_e32 v5, v5, v20, vcc
	v_rsq_f32_e32 v5, v5
	v_lshlrev_b32_e32 v20, 16, v6
	v_lshlrev_b32_e32 v6, 16, v7
	v_and_b32_e32 v7, 0xffff0000, v7
	v_mul_f32_e32 v24, 0x45800000, v5
	v_cndmask_b32_e32 v24, v5, v24, vcc
	v_lshlrev_b32_e32 v22, 16, v8
	v_and_b32_e32 v23, 0xffff0000, v8
	v_lshlrev_b32_e32 v8, 16, v9
	v_and_b32_e32 v9, 0xffff0000, v9
	v_pk_mul_f32 v[20:21], v[24:25], v[20:21] op_sel_hi:[0,1]
	v_pk_mul_f32 v[26:27], v[24:25], v[6:7] op_sel_hi:[0,1]
	v_pk_mul_f32 v[22:23], v[24:25], v[22:23] op_sel_hi:[0,1]
	v_pk_mul_f32 v[24:25], v[24:25], v[8:9] op_sel_hi:[0,1]
	v_pk_mul_f32 v[6:7], v[10:11], v[20:21]
	v_pk_mul_f32 v[8:9], v[12:13], v[26:27]
	v_pk_mul_f32 v[10:11], v[14:15], v[22:23]
	v_pk_mul_f32 v[12:13], v[16:17], v[24:25]
	global_store_dwordx4 v[18:19], v[6:9], off
	global_store_dwordx4 v[18:19], v[10:13], off offset:16
	s_andn2_b64 exec, exec, s[8:9]
	s_cbranch_execnz .Lp8_loop_sample
	s_mov_b64 exec, -1
	s_branch .LBB0_1563
.Lp8_generic:
	s_mov_b32 s3, 0
	s_lshl_b64 s[0:1], s[2:3], 9
	v_mov_b32_e32 v137, 0
	s_waitcnt lgkmcnt(0)
	v_lshl_add_u64 v[0:1], s[0:1], 0, v[136:137]
	s_mov_b64 s[0:1], 0x440000
	v_cmp_gt_u64_e32 vcc, s[0:1], v[0:1]
	s_and_saveexec_b64 s[0:1], vcc
	s_cbranch_execz .LBB0_1563
	s_add_u32 s0, s44, 0x5e64000
	s_addc_u32 s1, s45, 0
	s_add_u32 s4, s44, 0x1a20000
	s_addc_u32 s5, s45, 0
	s_mov_b32 s95, s3
	s_lshl_b64 s[2:3], s[2:3], 12
	v_lshlrev_b32_e32 v136, 3, v136
	s_lshl_b64 s[6:7], s[94:95], 9
	v_lshl_add_u64 v[2:3], s[2:3], 0, v[136:137]
	s_lshl_b64 s[2:3], s[94:95], 12
	s_mov_b64 s[8:9], 0
	v_mov_b32_e32 v4, 0x358637bd
	s_mov_b32 s12, 0x800000
	s_mov_b64 s[10:11], 0x43ffff
